# v30 + attention main loop DMA issue block: dropped the m0 save/restore pairs around the four LDS-DMA issues (m0 has no other reader)
# speedup vs baseline: 1.0052x; 1.0052x over previous
; __device__ __forceinline__ void glds16(const void* gsrc, unsigned lds_dst) { unsigned keep;
;     asm volatile("s_mov_b32 %0, m0\n\ts_mov_b32 m0, %2\n\ts_nop 0\n\tglobal_load_lds_dwordx4 %1, off\n\ts_mov_b32 m0, %0" : "=&s"(keep) : "v"(gsrc), "s"(lds_dst) : "memory"); }
.LBB0_638:
	s_add_i32 s19, s75, 0xffffc000
	s_cmp_lg_u32 s76, 0
	s_cselect_b32 s19, s19, 0xc000
	s_add_i32 s19, s19, 0
	s_add_i32 s74, s19, s28
	s_mov_b32 m0, s74
	s_nop 0
	global_load_lds_dwordx4 v[138:139], off
	s_add_i32 s74, s19, s73
	s_mov_b32 m0, s74
	s_nop 0
	global_load_lds_dwordx4 v[136:137], off
	s_add_i32 s19, s19, 0x10000
	s_add_i32 s74, s19, s28
	s_mov_b32 m0, s74
	s_nop 0
	global_load_lds_dwordx4 v[134:135], off
	s_add_i32 s19, s19, s73
	s_mov_b32 m0, s19
	s_nop 0
	global_load_lds_dwordx4 v[132:133], off
